# P6 epilogue: coalesced stores issued progressively (software-pipelined with relu/cvt/bpermute), ALIGN barrier after 4 of 16 groups
# speedup vs baseline: 1.0163x; 1.0071x over previous
.LBB0_961:
	ds_read_b128 v[144:147], v155
	ds_read_b128 v[148:151], v155 offset:1024
	ds_read_b128 v[158:161], v155 offset:2048
	ds_read_b128 v[162:165], v155 offset:3072
	ds_read_b128 v[166:169], v156
	ds_read_b128 v[170:173], v156 offset:1024
	ds_read_b128 v[174:177], v156 offset:2048
	ds_read_b128 v[178:181], v156 offset:3072
	s_add_i32 s78, s10, 2
	s_add_u32 s33, s46, 0x80
	s_addc_u32 s11, s47, 0
	s_cmp_eq_u32 s65, s10
	s_cselect_b32 s10, s4, s33
	s_cselect_b32 s11, s5, s11
	s_cselect_b32 s81, s45, s49
	s_cselect_b32 s80, s44, s48
	v_lshl_add_u64 v[218:219], s[46:47], 0, v[136:137]
	s_add_i32 m0, s35, 0xc000
	ds_read_b128 v[182:185], v157
	ds_read_b128 v[186:189], v157 offset:1024
	ds_read_b128 v[190:193], v157 offset:2048
	ds_read_b128 v[194:197], v157 offset:3072
	ds_read_b128 v[198:201], v157 offset:4096
	ds_read_b128 v[204:207], v157 offset:5120
	ds_read_b128 v[210:213], v157 offset:6144
	ds_read_b128 v[214:217], v157 offset:7168
	global_load_lds_dwordx4 v[218:219], off
	v_lshl_add_u64 v[218:219], s[46:47], 0, v[138:139]
	s_add_i32 m0, s35, 0xe000
	s_nop 0
	global_load_lds_dwordx4 v[218:219], off
	s_waitcnt vmcnt(8)
	s_waitcnt lgkmcnt(0)
	s_barrier
	s_setprio 1
	s_waitcnt lgkmcnt(0)
	v_mfma_f32_16x16x32_bf16 v[124:127], v[144:147], v[182:185], v[124:127]
	v_mfma_f32_16x16x32_bf16 v[120:123], v[158:161], v[182:185], v[120:123]
	v_mfma_f32_16x16x32_bf16 v[116:119], v[144:147], v[190:193], v[116:119]
	v_mfma_f32_16x16x32_bf16 v[108:111], v[158:161], v[190:193], v[108:111]
	v_mfma_f32_16x16x32_bf16 v[100:103], v[144:147], v[198:201], v[100:103]
	v_mfma_f32_16x16x32_bf16 v[92:95], v[158:161], v[198:201], v[92:95]
	v_mfma_f32_16x16x32_bf16 v[84:87], v[144:147], v[210:213], v[84:87]
	v_mfma_f32_16x16x32_bf16 v[76:79], v[158:161], v[210:213], v[76:79]
	v_mfma_f32_16x16x32_bf16 v[124:127], v[148:151], v[186:189], v[124:127]
	v_mfma_f32_16x16x32_bf16 v[120:123], v[162:165], v[186:189], v[120:123]
	v_mfma_f32_16x16x32_bf16 v[116:119], v[148:151], v[194:197], v[116:119]
	v_mfma_f32_16x16x32_bf16 v[108:111], v[162:165], v[194:197], v[108:111]
	v_mfma_f32_16x16x32_bf16 v[100:103], v[148:151], v[204:207], v[100:103]
	v_mfma_f32_16x16x32_bf16 v[92:95], v[162:165], v[204:207], v[92:95]
	v_mfma_f32_16x16x32_bf16 v[84:87], v[148:151], v[214:217], v[84:87]
	v_mfma_f32_16x16x32_bf16 v[76:79], v[162:165], v[214:217], v[76:79]
	s_setprio 0
	s_setprio 1
	v_mfma_f32_16x16x32_bf16 v[112:115], v[166:169], v[182:185], v[112:115]
	v_mfma_f32_16x16x32_bf16 v[104:107], v[174:177], v[182:185], v[104:107]
	v_mfma_f32_16x16x32_bf16 v[96:99], v[166:169], v[190:193], v[96:99]
	v_mfma_f32_16x16x32_bf16 v[88:91], v[174:177], v[190:193], v[88:91]
	v_mfma_f32_16x16x32_bf16 v[80:83], v[166:169], v[198:201], v[80:83]
	v_mfma_f32_16x16x32_bf16 v[72:75], v[174:177], v[198:201], v[72:75]
	v_mfma_f32_16x16x32_bf16 v[68:71], v[166:169], v[210:213], v[68:71]
	v_mfma_f32_16x16x32_bf16 v[64:67], v[174:177], v[210:213], v[64:67]
	v_mfma_f32_16x16x32_bf16 v[112:115], v[170:173], v[186:189], v[112:115]
	v_mfma_f32_16x16x32_bf16 v[104:107], v[178:181], v[186:189], v[104:107]
	v_mfma_f32_16x16x32_bf16 v[96:99], v[170:173], v[194:197], v[96:99]
	v_mfma_f32_16x16x32_bf16 v[88:91], v[178:181], v[194:197], v[88:91]
	v_mfma_f32_16x16x32_bf16 v[80:83], v[170:173], v[204:207], v[80:83]
	v_mfma_f32_16x16x32_bf16 v[72:75], v[178:181], v[204:207], v[72:75]
	v_mfma_f32_16x16x32_bf16 v[68:71], v[170:173], v[214:217], v[68:71]
	v_mfma_f32_16x16x32_bf16 v[64:67], v[178:181], v[214:217], v[64:67]
	s_setprio 0
	s_barrier
	s_add_i32 s33, s68, s34
	v_lshl_add_u64 v[218:219], s[80:81], 0, v[130:131]
	s_mov_b32 m0, s33
	ds_read_b128 v[182:185], v157 offset:16384
	ds_read_b128 v[186:189], v157 offset:17408
	ds_read_b128 v[190:193], v157 offset:18432
	ds_read_b128 v[194:197], v157 offset:19456
	ds_read_b128 v[198:201], v157 offset:20480
	ds_read_b128 v[204:207], v157 offset:21504
	ds_read_b128 v[210:213], v157 offset:22528
	ds_read_b128 v[214:217], v157 offset:23552
	global_load_lds_dwordx4 v[218:219], off
	s_add_i32 m0, s33, 0x2000
	v_lshl_add_u64 v[220:221], s[80:81], 0, v[134:135]
	s_add_u32 s80, s80, s16
	s_addc_u32 s81, s81, s17
	s_add_i32 s33, s69, s34
	global_load_lds_dwordx4 v[220:221], off
	v_lshl_add_u64 v[222:223], s[80:81], 0, v[130:131]
	s_mov_b32 m0, s33
	v_lshl_add_u64 v[224:225], s[80:81], 0, v[134:135]
	global_load_lds_dwordx4 v[222:223], off
	s_add_i32 m0, s33, 0x2000
	v_lshl_add_u64 v[226:227], s[10:11], 0, v[128:129]
	global_load_lds_dwordx4 v[224:225], off
	s_mov_b32 m0, s35
	v_lshl_add_u64 v[228:229], s[10:11], 0, v[132:133]
	global_load_lds_dwordx4 v[226:227], off
	s_mov_b32 m0, s50
	s_nop 0
	global_load_lds_dwordx4 v[228:229], off
	s_waitcnt vmcnt(8)
	s_waitcnt lgkmcnt(0)
	s_barrier
	s_setprio 1
	s_waitcnt lgkmcnt(0)
	v_mfma_f32_16x16x32_bf16 v[60:63], v[144:147], v[182:185], v[60:63]
	v_mfma_f32_16x16x32_bf16 v[56:59], v[158:161], v[182:185], v[56:59]
	v_mfma_f32_16x16x32_bf16 v[52:55], v[144:147], v[190:193], v[52:55]
	v_mfma_f32_16x16x32_bf16 v[44:47], v[158:161], v[190:193], v[44:47]
	v_mfma_f32_16x16x32_bf16 v[36:39], v[144:147], v[198:201], v[36:39]
	v_mfma_f32_16x16x32_bf16 v[28:31], v[158:161], v[198:201], v[28:31]
	v_mfma_f32_16x16x32_bf16 v[20:23], v[144:147], v[210:213], v[20:23]
	v_mfma_f32_16x16x32_bf16 v[12:15], v[158:161], v[210:213], v[12:15]
	v_mfma_f32_16x16x32_bf16 v[60:63], v[148:151], v[186:189], v[60:63]
	v_mfma_f32_16x16x32_bf16 v[56:59], v[162:165], v[186:189], v[56:59]
	v_mfma_f32_16x16x32_bf16 v[52:55], v[148:151], v[194:197], v[52:55]
	v_mfma_f32_16x16x32_bf16 v[44:47], v[162:165], v[194:197], v[44:47]
	v_mfma_f32_16x16x32_bf16 v[36:39], v[148:151], v[204:207], v[36:39]
	v_mfma_f32_16x16x32_bf16 v[28:31], v[162:165], v[204:207], v[28:31]
	v_mfma_f32_16x16x32_bf16 v[20:23], v[148:151], v[214:217], v[20:23]
	v_mfma_f32_16x16x32_bf16 v[12:15], v[162:165], v[214:217], v[12:15]
	s_setprio 0
	s_setprio 1
	v_mfma_f32_16x16x32_bf16 v[48:51], v[166:169], v[182:185], v[48:51]
	v_mfma_f32_16x16x32_bf16 v[40:43], v[174:177], v[182:185], v[40:43]
	v_mfma_f32_16x16x32_bf16 v[32:35], v[166:169], v[190:193], v[32:35]
	v_mfma_f32_16x16x32_bf16 v[24:27], v[174:177], v[190:193], v[24:27]
	v_mfma_f32_16x16x32_bf16 v[16:19], v[166:169], v[198:201], v[16:19]
	v_mfma_f32_16x16x32_bf16 v[8:11], v[174:177], v[198:201], v[8:11]
	v_mfma_f32_16x16x32_bf16 v[4:7], v[166:169], v[210:213], v[4:7]
	v_mfma_f32_16x16x32_bf16 v[0:3], v[174:177], v[210:213], v[0:3]
	v_mfma_f32_16x16x32_bf16 v[48:51], v[170:173], v[186:189], v[48:51]
	v_mfma_f32_16x16x32_bf16 v[40:43], v[178:181], v[186:189], v[40:43]
	v_mfma_f32_16x16x32_bf16 v[32:35], v[170:173], v[194:197], v[32:35]
	v_mfma_f32_16x16x32_bf16 v[24:27], v[178:181], v[194:197], v[24:27]
	v_mfma_f32_16x16x32_bf16 v[16:19], v[170:173], v[204:207], v[16:19]
	v_mfma_f32_16x16x32_bf16 v[8:11], v[178:181], v[204:207], v[8:11]
	v_mfma_f32_16x16x32_bf16 v[4:7], v[170:173], v[214:217], v[4:7]
	v_mfma_f32_16x16x32_bf16 v[0:3], v[178:181], v[214:217], v[0:3]
	s_setprio 0
	s_barrier
	s_add_i32 s33, 0, 0x18000
	s_add_i32 s79, 0, 0x1c000
	v_add_u32_e32 v162, s33, v153
	v_add_u32_e32 v178, s79, v153
	ds_read_b128 v[144:147], v162
	ds_read_b128 v[148:151], v162 offset:1024
	ds_read_b128 v[158:161], v162 offset:2048
	ds_read_b128 v[162:165], v162 offset:3072
	ds_read_b128 v[166:169], v178
	ds_read_b128 v[170:173], v178 offset:1024
	ds_read_b128 v[174:177], v178 offset:2048
	ds_read_b128 v[178:181], v178 offset:3072
	s_add_u32 s10, s10, s16
	s_addc_u32 s11, s11, s17
	s_mov_b32 m0, s51
	v_lshl_add_u64 v[230:231], s[10:11], 0, v[128:129]
	ds_read_b128 v[182:185], v157 offset:32768
	ds_read_b128 v[186:189], v157 offset:33792
	ds_read_b128 v[190:193], v157 offset:34816
	ds_read_b128 v[194:197], v157 offset:35840
	ds_read_b128 v[198:201], v157 offset:36864
	ds_read_b128 v[204:207], v157 offset:37888
	ds_read_b128 v[210:213], v157 offset:38912
	ds_read_b128 v[214:217], v157 offset:39936
	global_load_lds_dwordx4 v[230:231], off
	v_lshl_add_u64 v[230:231], s[10:11], 0, v[132:133]
	s_mov_b32 m0, s52
	s_nop 0
	global_load_lds_dwordx4 v[230:231], off
	s_waitcnt vmcnt(8)
	s_waitcnt lgkmcnt(0)
	s_barrier
	s_setprio 1
	s_waitcnt lgkmcnt(0)
	v_mfma_f32_16x16x32_bf16 v[124:127], v[144:147], v[182:185], v[124:127]
	v_mfma_f32_16x16x32_bf16 v[120:123], v[158:161], v[182:185], v[120:123]
	v_mfma_f32_16x16x32_bf16 v[116:119], v[144:147], v[190:193], v[116:119]
	v_mfma_f32_16x16x32_bf16 v[108:111], v[158:161], v[190:193], v[108:111]
	v_mfma_f32_16x16x32_bf16 v[100:103], v[144:147], v[198:201], v[100:103]
	v_mfma_f32_16x16x32_bf16 v[92:95], v[158:161], v[198:201], v[92:95]
	v_mfma_f32_16x16x32_bf16 v[84:87], v[144:147], v[210:213], v[84:87]
	v_mfma_f32_16x16x32_bf16 v[76:79], v[158:161], v[210:213], v[76:79]
	v_mfma_f32_16x16x32_bf16 v[124:127], v[148:151], v[186:189], v[124:127]
	v_mfma_f32_16x16x32_bf16 v[120:123], v[162:165], v[186:189], v[120:123]
	v_mfma_f32_16x16x32_bf16 v[116:119], v[148:151], v[194:197], v[116:119]
	v_mfma_f32_16x16x32_bf16 v[108:111], v[162:165], v[194:197], v[108:111]
	v_mfma_f32_16x16x32_bf16 v[100:103], v[148:151], v[204:207], v[100:103]
	v_mfma_f32_16x16x32_bf16 v[92:95], v[162:165], v[204:207], v[92:95]
	v_mfma_f32_16x16x32_bf16 v[84:87], v[148:151], v[214:217], v[84:87]
	v_mfma_f32_16x16x32_bf16 v[76:79], v[162:165], v[214:217], v[76:79]
	s_setprio 0
	s_setprio 1
	v_mfma_f32_16x16x32_bf16 v[112:115], v[166:169], v[182:185], v[112:115]
	v_mfma_f32_16x16x32_bf16 v[104:107], v[174:177], v[182:185], v[104:107]
	v_mfma_f32_16x16x32_bf16 v[96:99], v[166:169], v[190:193], v[96:99]
	v_mfma_f32_16x16x32_bf16 v[88:91], v[174:177], v[190:193], v[88:91]
	v_mfma_f32_16x16x32_bf16 v[80:83], v[166:169], v[198:201], v[80:83]
	v_mfma_f32_16x16x32_bf16 v[72:75], v[174:177], v[198:201], v[72:75]
	v_mfma_f32_16x16x32_bf16 v[68:71], v[166:169], v[210:213], v[68:71]
	v_mfma_f32_16x16x32_bf16 v[64:67], v[174:177], v[210:213], v[64:67]
	v_mfma_f32_16x16x32_bf16 v[112:115], v[170:173], v[186:189], v[112:115]
	v_mfma_f32_16x16x32_bf16 v[104:107], v[178:181], v[186:189], v[104:107]
	v_mfma_f32_16x16x32_bf16 v[96:99], v[170:173], v[194:197], v[96:99]
	v_mfma_f32_16x16x32_bf16 v[88:91], v[178:181], v[194:197], v[88:91]
	v_mfma_f32_16x16x32_bf16 v[80:83], v[170:173], v[204:207], v[80:83]
	v_mfma_f32_16x16x32_bf16 v[72:75], v[178:181], v[204:207], v[72:75]
	v_mfma_f32_16x16x32_bf16 v[68:71], v[170:173], v[214:217], v[68:71]
	v_mfma_f32_16x16x32_bf16 v[64:67], v[178:181], v[214:217], v[64:67]
	s_setprio 0
	s_barrier
	s_add_i32 s10, s33, s34
	v_lshl_add_u64 v[218:219], v[218:219], 0, s[22:23]
	s_mov_b32 m0, s10
	ds_read_b128 v[182:185], v157 offset:49152
	ds_read_b128 v[186:189], v157 offset:50176
	ds_read_b128 v[190:193], v157 offset:51200
	ds_read_b128 v[194:197], v157 offset:52224
	ds_read_b128 v[198:201], v157 offset:53248
	ds_read_b128 v[204:207], v157 offset:54272
	ds_read_b128 v[210:213], v157 offset:55296
	ds_read_b128 v[214:217], v157 offset:56320
	global_load_lds_dwordx4 v[218:219], off
	v_lshl_add_u64 v[218:219], v[220:221], 0, s[22:23]
	s_add_i32 m0, s10, 0x2000
	s_add_i32 s10, s79, s34
	global_load_lds_dwordx4 v[218:219], off
	v_lshl_add_u64 v[218:219], v[222:223], 0, s[22:23]
	s_mov_b32 m0, s10
	s_nop 0
	global_load_lds_dwordx4 v[218:219], off
	v_lshl_add_u64 v[218:219], v[224:225], 0, s[22:23]
	s_add_i32 m0, s10, 0x2000
	s_nop 0
	global_load_lds_dwordx4 v[218:219], off
	v_lshl_add_u64 v[218:219], v[226:227], 0, s[22:23]
	s_mov_b32 m0, s62
	s_nop 0
	global_load_lds_dwordx4 v[218:219], off
	v_lshl_add_u64 v[218:219], v[228:229], 0, s[22:23]
	s_mov_b32 m0, s63
	s_nop 0
	global_load_lds_dwordx4 v[218:219], off
	s_waitcnt vmcnt(8)
	s_waitcnt lgkmcnt(0)
	s_barrier
	s_setprio 1
	s_waitcnt lgkmcnt(0)
	v_mfma_f32_16x16x32_bf16 v[60:63], v[144:147], v[182:185], v[60:63]
	v_mfma_f32_16x16x32_bf16 v[56:59], v[158:161], v[182:185], v[56:59]
	v_mfma_f32_16x16x32_bf16 v[52:55], v[144:147], v[190:193], v[52:55]
	v_mfma_f32_16x16x32_bf16 v[44:47], v[158:161], v[190:193], v[44:47]
	v_mfma_f32_16x16x32_bf16 v[36:39], v[144:147], v[198:201], v[36:39]
	v_mfma_f32_16x16x32_bf16 v[28:31], v[158:161], v[198:201], v[28:31]
	v_mfma_f32_16x16x32_bf16 v[20:23], v[144:147], v[210:213], v[20:23]
	v_mfma_f32_16x16x32_bf16 v[12:15], v[158:161], v[210:213], v[12:15]
	v_mfma_f32_16x16x32_bf16 v[60:63], v[148:151], v[186:189], v[60:63]
	v_mfma_f32_16x16x32_bf16 v[56:59], v[162:165], v[186:189], v[56:59]
	v_mfma_f32_16x16x32_bf16 v[52:55], v[148:151], v[194:197], v[52:55]
	v_mfma_f32_16x16x32_bf16 v[44:47], v[162:165], v[194:197], v[44:47]
	v_mfma_f32_16x16x32_bf16 v[36:39], v[148:151], v[204:207], v[36:39]
	v_mfma_f32_16x16x32_bf16 v[28:31], v[162:165], v[204:207], v[28:31]
	v_mfma_f32_16x16x32_bf16 v[20:23], v[148:151], v[214:217], v[20:23]
	v_mfma_f32_16x16x32_bf16 v[12:15], v[162:165], v[214:217], v[12:15]
	s_setprio 0
	s_setprio 1
	v_mfma_f32_16x16x32_bf16 v[48:51], v[166:169], v[182:185], v[48:51]
	v_mfma_f32_16x16x32_bf16 v[40:43], v[174:177], v[182:185], v[40:43]
	v_mfma_f32_16x16x32_bf16 v[32:35], v[166:169], v[190:193], v[32:35]
	v_mfma_f32_16x16x32_bf16 v[24:27], v[174:177], v[190:193], v[24:27]
	v_mfma_f32_16x16x32_bf16 v[16:19], v[166:169], v[198:201], v[16:19]
	v_mfma_f32_16x16x32_bf16 v[8:11], v[174:177], v[198:201], v[8:11]
	v_mfma_f32_16x16x32_bf16 v[4:7], v[166:169], v[210:213], v[4:7]
	v_mfma_f32_16x16x32_bf16 v[0:3], v[174:177], v[210:213], v[0:3]
	v_mfma_f32_16x16x32_bf16 v[48:51], v[170:173], v[186:189], v[48:51]
	v_mfma_f32_16x16x32_bf16 v[40:43], v[178:181], v[186:189], v[40:43]
	v_mfma_f32_16x16x32_bf16 v[32:35], v[170:173], v[194:197], v[32:35]
	v_mfma_f32_16x16x32_bf16 v[24:27], v[178:181], v[194:197], v[24:27]
	v_mfma_f32_16x16x32_bf16 v[16:19], v[170:173], v[204:207], v[16:19]
	v_mfma_f32_16x16x32_bf16 v[8:11], v[178:181], v[204:207], v[8:11]
	v_mfma_f32_16x16x32_bf16 v[4:7], v[170:173], v[214:217], v[4:7]
	v_mfma_f32_16x16x32_bf16 v[0:3], v[178:181], v[214:217], v[0:3]
	s_setprio 0
	s_barrier
	s_add_u32 s46, s46, 0x100
	s_addc_u32 s47, s47, 0
	s_add_u32 s48, s48, 0x100
	s_addc_u32 s49, s49, 0
	s_cmp_ge_i32 s78, s64
	s_mov_b32 s10, s78
	s_cbranch_scc0 .LBB0_961
	v_and_b32_e32 v144, 3, v209
	v_bfe_u32 v145, v209, 4, 2
	v_and_or_b32 v146, v209, 12, v145
	v_lshl_or_b32 v147, v144, 4, v146
	v_lshlrev_b32_e32 v147, 2, v147
	v_and_or_b32 v148, v152, -16, v146
	v_and_b32_e32 v149, 0x60, v154
	v_lshl_or_b32 v149, v144, 3, v149
	s_mov_b64 vcc, 0x20000
	v_lshl_add_u32 v148, s76, 8, v148
	v_lshl_or_b32 v149, s77, 8, v149
	v_lshlrev_b32_e32 v148, 13, v148
	v_lshl_add_u32 v150, v149, 1, v148
	v_mov_b32_e32 v151, 0
	v_lshl_add_u64 v[158:159], s[30:31], 0, v[150:151]
	v_lshl_add_u64 v[160:161], v[158:159], 0, vcc
	v_lshl_add_u64 v[162:163], v[160:161], 0, vcc
	v_lshl_add_u64 v[164:165], v[162:163], 0, vcc
	v_lshl_add_u64 v[166:167], v[158:159], 0, s[36:37]
	v_lshl_add_u64 v[168:169], v[160:161], 0, s[36:37]
	v_lshl_add_u64 v[170:171], v[162:163], 0, s[36:37]
	v_lshl_add_u64 v[172:173], v[164:165], 0, s[36:37]
	v_max_f32_e32 v124, 0, v124
	v_max_f32_e32 v125, 0, v125
	v_max_f32_e32 v126, 0, v126
	v_max_f32_e32 v127, 0, v127
	v_max_f32_e32 v120, 0, v120
	v_max_f32_e32 v121, 0, v121
	v_max_f32_e32 v122, 0, v122
	v_max_f32_e32 v123, 0, v123
	v_pk_mul_f32 v[124:125], v[124:125], v[124:125]
	v_pk_mul_f32 v[126:127], v[126:127], v[126:127]
	v_pk_mul_f32 v[120:121], v[120:121], v[120:121]
	v_pk_mul_f32 v[122:123], v[122:123], v[122:123]
	v_cvt_pk_bf16_f32 v124, v124, v125
	v_cvt_pk_bf16_f32 v125, v126, v127
	v_cvt_pk_bf16_f32 v126, v120, v121
	v_cvt_pk_bf16_f32 v127, v122, v123
	ds_bpermute_b32 v124, v147, v124
	ds_bpermute_b32 v125, v147, v125
	ds_bpermute_b32 v126, v147, v126
	ds_bpermute_b32 v127, v147, v127
	v_max_f32_e32 v116, 0, v116
	v_max_f32_e32 v117, 0, v117
	v_max_f32_e32 v118, 0, v118
	v_max_f32_e32 v119, 0, v119
	v_max_f32_e32 v108, 0, v108
	v_max_f32_e32 v109, 0, v109
	v_max_f32_e32 v110, 0, v110
	v_max_f32_e32 v111, 0, v111
	v_pk_mul_f32 v[116:117], v[116:117], v[116:117]
	v_pk_mul_f32 v[118:119], v[118:119], v[118:119]
	v_pk_mul_f32 v[108:109], v[108:109], v[108:109]
	v_pk_mul_f32 v[110:111], v[110:111], v[110:111]
	v_cvt_pk_bf16_f32 v116, v116, v117
	v_cvt_pk_bf16_f32 v117, v118, v119
	v_cvt_pk_bf16_f32 v118, v108, v109
	v_cvt_pk_bf16_f32 v119, v110, v111
	ds_bpermute_b32 v116, v147, v116
	ds_bpermute_b32 v117, v147, v117
	ds_bpermute_b32 v118, v147, v118
	ds_bpermute_b32 v119, v147, v119
	v_max_f32_e32 v100, 0, v100
	v_max_f32_e32 v101, 0, v101
	v_max_f32_e32 v102, 0, v102
	v_max_f32_e32 v103, 0, v103
	v_max_f32_e32 v92, 0, v92
	v_max_f32_e32 v93, 0, v93
	v_max_f32_e32 v94, 0, v94
	v_max_f32_e32 v95, 0, v95
	v_pk_mul_f32 v[100:101], v[100:101], v[100:101]
	v_pk_mul_f32 v[102:103], v[102:103], v[102:103]
	v_pk_mul_f32 v[92:93], v[92:93], v[92:93]
	v_pk_mul_f32 v[94:95], v[94:95], v[94:95]
	v_cvt_pk_bf16_f32 v100, v100, v101
	v_cvt_pk_bf16_f32 v101, v102, v103
	v_cvt_pk_bf16_f32 v102, v92, v93
	v_cvt_pk_bf16_f32 v103, v94, v95
	ds_bpermute_b32 v100, v147, v100
	ds_bpermute_b32 v101, v147, v101
	ds_bpermute_b32 v102, v147, v102
	ds_bpermute_b32 v103, v147, v103
	s_waitcnt lgkmcnt(8)
	global_store_dwordx4 v[158:159], v[124:127], off nt
	v_max_f32_e32 v84, 0, v84
	v_max_f32_e32 v85, 0, v85
	v_max_f32_e32 v86, 0, v86
	v_max_f32_e32 v87, 0, v87
	v_max_f32_e32 v76, 0, v76
	v_max_f32_e32 v77, 0, v77
	v_max_f32_e32 v78, 0, v78
	v_max_f32_e32 v79, 0, v79
	v_pk_mul_f32 v[84:85], v[84:85], v[84:85]
	v_pk_mul_f32 v[86:87], v[86:87], v[86:87]
	v_pk_mul_f32 v[76:77], v[76:77], v[76:77]
	v_pk_mul_f32 v[78:79], v[78:79], v[78:79]
	v_cvt_pk_bf16_f32 v84, v84, v85
	v_cvt_pk_bf16_f32 v85, v86, v87
	v_cvt_pk_bf16_f32 v86, v76, v77
	v_cvt_pk_bf16_f32 v87, v78, v79
	ds_bpermute_b32 v84, v147, v84
	ds_bpermute_b32 v85, v147, v85
	ds_bpermute_b32 v86, v147, v86
	ds_bpermute_b32 v87, v147, v87

.LBB0_965:
	s_waitcnt lgkmcnt(8)
	global_store_dwordx4 v[160:161], v[116:119], off nt
	v_max_f32_e32 v112, 0, v112
	v_max_f32_e32 v113, 0, v113
	v_max_f32_e32 v114, 0, v114
	v_max_f32_e32 v115, 0, v115
	v_max_f32_e32 v104, 0, v104
	v_max_f32_e32 v105, 0, v105
	v_max_f32_e32 v106, 0, v106
	v_max_f32_e32 v107, 0, v107
	v_pk_mul_f32 v[112:113], v[112:113], v[112:113]
	v_pk_mul_f32 v[114:115], v[114:115], v[114:115]
	v_pk_mul_f32 v[104:105], v[104:105], v[104:105]
	v_pk_mul_f32 v[106:107], v[106:107], v[106:107]
	v_cvt_pk_bf16_f32 v112, v112, v113
	v_cvt_pk_bf16_f32 v113, v114, v115
	v_cvt_pk_bf16_f32 v114, v104, v105
	v_cvt_pk_bf16_f32 v115, v106, v107
	ds_bpermute_b32 v112, v147, v112
	ds_bpermute_b32 v113, v147, v113
	ds_bpermute_b32 v114, v147, v114
	ds_bpermute_b32 v115, v147, v115
	s_waitcnt lgkmcnt(8)
	global_store_dwordx4 v[162:163], v[100:103], off nt
	v_max_f32_e32 v96, 0, v96
	v_max_f32_e32 v97, 0, v97
	v_max_f32_e32 v98, 0, v98
	v_max_f32_e32 v99, 0, v99
	v_max_f32_e32 v88, 0, v88
	v_max_f32_e32 v89, 0, v89
	v_max_f32_e32 v90, 0, v90
	v_max_f32_e32 v91, 0, v91
	v_pk_mul_f32 v[96:97], v[96:97], v[96:97]
	v_pk_mul_f32 v[98:99], v[98:99], v[98:99]
	v_pk_mul_f32 v[88:89], v[88:89], v[88:89]
	v_pk_mul_f32 v[90:91], v[90:91], v[90:91]
	v_cvt_pk_bf16_f32 v96, v96, v97
	v_cvt_pk_bf16_f32 v97, v98, v99
	v_cvt_pk_bf16_f32 v98, v88, v89
	v_cvt_pk_bf16_f32 v99, v90, v91
	ds_bpermute_b32 v96, v147, v96
	ds_bpermute_b32 v97, v147, v97
	ds_bpermute_b32 v98, v147, v98
	ds_bpermute_b32 v99, v147, v99
	s_waitcnt lgkmcnt(8)
	global_store_dwordx4 v[164:165], v[84:87], off nt
	v_max_f32_e32 v80, 0, v80
	v_max_f32_e32 v81, 0, v81
	v_max_f32_e32 v82, 0, v82
	v_max_f32_e32 v83, 0, v83
	v_max_f32_e32 v72, 0, v72
	v_max_f32_e32 v73, 0, v73
	v_max_f32_e32 v74, 0, v74
	v_max_f32_e32 v75, 0, v75
	v_pk_mul_f32 v[80:81], v[80:81], v[80:81]
	v_pk_mul_f32 v[82:83], v[82:83], v[82:83]
	v_pk_mul_f32 v[72:73], v[72:73], v[72:73]
	v_pk_mul_f32 v[74:75], v[74:75], v[74:75]
	v_cvt_pk_bf16_f32 v80, v80, v81
	v_cvt_pk_bf16_f32 v81, v82, v83
	v_cvt_pk_bf16_f32 v82, v72, v73
	v_cvt_pk_bf16_f32 v83, v74, v75
	ds_bpermute_b32 v80, v147, v80
	ds_bpermute_b32 v81, v147, v81
	ds_bpermute_b32 v82, v147, v82
	ds_bpermute_b32 v83, v147, v83
	s_waitcnt lgkmcnt(8)
	global_store_dwordx4 v[158:159], v[112:115], off offset:256 nt
	v_max_f32_e32 v68, 0, v68
	v_max_f32_e32 v69, 0, v69
	v_max_f32_e32 v70, 0, v70
	v_max_f32_e32 v71, 0, v71
	v_max_f32_e32 v64, 0, v64
	v_max_f32_e32 v65, 0, v65
	v_max_f32_e32 v66, 0, v66
	v_max_f32_e32 v67, 0, v67
	v_pk_mul_f32 v[68:69], v[68:69], v[68:69]
	v_pk_mul_f32 v[70:71], v[70:71], v[70:71]
	v_pk_mul_f32 v[64:65], v[64:65], v[64:65]
	v_pk_mul_f32 v[66:67], v[66:67], v[66:67]
	v_cvt_pk_bf16_f32 v68, v68, v69
	v_cvt_pk_bf16_f32 v69, v70, v71
	v_cvt_pk_bf16_f32 v70, v64, v65
	v_cvt_pk_bf16_f32 v71, v66, v67
	ds_bpermute_b32 v68, v147, v68
	ds_bpermute_b32 v69, v147, v69
	ds_bpermute_b32 v70, v147, v70
	ds_bpermute_b32 v71, v147, v71
	s_waitcnt lgkmcnt(8)
	global_store_dwordx4 v[160:161], v[96:99], off offset:256 nt
	v_max_f32_e32 v60, 0, v60
	v_max_f32_e32 v61, 0, v61
	v_max_f32_e32 v62, 0, v62
	v_max_f32_e32 v63, 0, v63
	v_max_f32_e32 v56, 0, v56
	v_max_f32_e32 v57, 0, v57
	v_max_f32_e32 v58, 0, v58
	v_max_f32_e32 v59, 0, v59
	v_pk_mul_f32 v[60:61], v[60:61], v[60:61]
	v_pk_mul_f32 v[62:63], v[62:63], v[62:63]
	v_pk_mul_f32 v[56:57], v[56:57], v[56:57]
	v_pk_mul_f32 v[58:59], v[58:59], v[58:59]
	v_cvt_pk_bf16_f32 v60, v60, v61
	v_cvt_pk_bf16_f32 v61, v62, v63
	v_cvt_pk_bf16_f32 v62, v56, v57
	v_cvt_pk_bf16_f32 v63, v58, v59
	ds_bpermute_b32 v60, v147, v60
	ds_bpermute_b32 v61, v147, v61
	ds_bpermute_b32 v62, v147, v62
	ds_bpermute_b32 v63, v147, v63
	s_waitcnt lgkmcnt(8)
	global_store_dwordx4 v[162:163], v[80:83], off offset:256 nt
	v_max_f32_e32 v52, 0, v52
	v_max_f32_e32 v53, 0, v53
	v_max_f32_e32 v54, 0, v54
	v_max_f32_e32 v55, 0, v55
	v_max_f32_e32 v44, 0, v44
	v_max_f32_e32 v45, 0, v45
	v_max_f32_e32 v46, 0, v46
	v_max_f32_e32 v47, 0, v47
	v_pk_mul_f32 v[52:53], v[52:53], v[52:53]
	v_pk_mul_f32 v[54:55], v[54:55], v[54:55]
	v_pk_mul_f32 v[44:45], v[44:45], v[44:45]
	v_pk_mul_f32 v[46:47], v[46:47], v[46:47]
	v_cvt_pk_bf16_f32 v52, v52, v53
	v_cvt_pk_bf16_f32 v53, v54, v55
	v_cvt_pk_bf16_f32 v54, v44, v45
	v_cvt_pk_bf16_f32 v55, v46, v47
	ds_bpermute_b32 v52, v147, v52
	ds_bpermute_b32 v53, v147, v53
	ds_bpermute_b32 v54, v147, v54
	ds_bpermute_b32 v55, v147, v55
	s_waitcnt lgkmcnt(8)
	global_store_dwordx4 v[164:165], v[68:71], off offset:256 nt
	v_max_f32_e32 v36, 0, v36
	v_max_f32_e32 v37, 0, v37
	v_max_f32_e32 v38, 0, v38
	v_max_f32_e32 v39, 0, v39
	v_max_f32_e32 v28, 0, v28
	v_max_f32_e32 v29, 0, v29
	v_max_f32_e32 v30, 0, v30
	v_max_f32_e32 v31, 0, v31
	v_pk_mul_f32 v[36:37], v[36:37], v[36:37]
	v_pk_mul_f32 v[38:39], v[38:39], v[38:39]
	v_pk_mul_f32 v[28:29], v[28:29], v[28:29]
	v_pk_mul_f32 v[30:31], v[30:31], v[30:31]
	v_cvt_pk_bf16_f32 v36, v36, v37
	v_cvt_pk_bf16_f32 v37, v38, v39
	v_cvt_pk_bf16_f32 v38, v28, v29
	v_cvt_pk_bf16_f32 v39, v30, v31
	ds_bpermute_b32 v36, v147, v36
	ds_bpermute_b32 v37, v147, v37
	ds_bpermute_b32 v38, v147, v38
	ds_bpermute_b32 v39, v147, v39
	s_waitcnt lgkmcnt(8)
	global_store_dwordx4 v[166:167], v[60:63], off nt
	v_max_f32_e32 v20, 0, v20
	v_max_f32_e32 v21, 0, v21
	v_max_f32_e32 v22, 0, v22
	v_max_f32_e32 v23, 0, v23
	v_max_f32_e32 v12, 0, v12
	v_max_f32_e32 v13, 0, v13
	v_max_f32_e32 v14, 0, v14
	v_max_f32_e32 v15, 0, v15
	v_pk_mul_f32 v[20:21], v[20:21], v[20:21]
	v_pk_mul_f32 v[22:23], v[22:23], v[22:23]
	v_pk_mul_f32 v[12:13], v[12:13], v[12:13]
	v_pk_mul_f32 v[14:15], v[14:15], v[14:15]
	v_cvt_pk_bf16_f32 v20, v20, v21
	v_cvt_pk_bf16_f32 v21, v22, v23
	v_cvt_pk_bf16_f32 v22, v12, v13
	v_cvt_pk_bf16_f32 v23, v14, v15
	ds_bpermute_b32 v20, v147, v20
	ds_bpermute_b32 v21, v147, v21
	ds_bpermute_b32 v22, v147, v22
	ds_bpermute_b32 v23, v147, v23
	s_waitcnt lgkmcnt(8)
	global_store_dwordx4 v[168:169], v[52:55], off nt
	v_max_f32_e32 v48, 0, v48
	v_max_f32_e32 v49, 0, v49
	v_max_f32_e32 v50, 0, v50
	v_max_f32_e32 v51, 0, v51
	v_max_f32_e32 v40, 0, v40
	v_max_f32_e32 v41, 0, v41
	v_max_f32_e32 v42, 0, v42
	v_max_f32_e32 v43, 0, v43
	v_pk_mul_f32 v[48:49], v[48:49], v[48:49]
	v_pk_mul_f32 v[50:51], v[50:51], v[50:51]
	v_pk_mul_f32 v[40:41], v[40:41], v[40:41]
	v_pk_mul_f32 v[42:43], v[42:43], v[42:43]
	v_cvt_pk_bf16_f32 v48, v48, v49
	v_cvt_pk_bf16_f32 v49, v50, v51
	v_cvt_pk_bf16_f32 v50, v40, v41
	v_cvt_pk_bf16_f32 v51, v42, v43
	ds_bpermute_b32 v48, v147, v48
	ds_bpermute_b32 v49, v147, v49
	ds_bpermute_b32 v50, v147, v50
	ds_bpermute_b32 v51, v147, v51
	s_waitcnt lgkmcnt(8)
	global_store_dwordx4 v[170:171], v[36:39], off nt
	v_max_f32_e32 v32, 0, v32
	v_max_f32_e32 v33, 0, v33
	v_max_f32_e32 v34, 0, v34
	v_max_f32_e32 v35, 0, v35
	v_max_f32_e32 v24, 0, v24
	v_max_f32_e32 v25, 0, v25
	v_max_f32_e32 v26, 0, v26
	v_max_f32_e32 v27, 0, v27
	v_pk_mul_f32 v[32:33], v[32:33], v[32:33]
	v_pk_mul_f32 v[34:35], v[34:35], v[34:35]
	v_pk_mul_f32 v[24:25], v[24:25], v[24:25]
	v_pk_mul_f32 v[26:27], v[26:27], v[26:27]
	v_cvt_pk_bf16_f32 v32, v32, v33
	v_cvt_pk_bf16_f32 v33, v34, v35
	v_cvt_pk_bf16_f32 v34, v24, v25
	v_cvt_pk_bf16_f32 v35, v26, v27
	ds_bpermute_b32 v32, v147, v32
	ds_bpermute_b32 v33, v147, v33
	ds_bpermute_b32 v34, v147, v34
	ds_bpermute_b32 v35, v147, v35
	s_waitcnt lgkmcnt(8)
	global_store_dwordx4 v[172:173], v[20:23], off nt
	v_max_f32_e32 v16, 0, v16
	v_max_f32_e32 v17, 0, v17
	v_max_f32_e32 v18, 0, v18
	v_max_f32_e32 v19, 0, v19
	v_max_f32_e32 v8, 0, v8
	v_max_f32_e32 v9, 0, v9
	v_max_f32_e32 v10, 0, v10
	v_max_f32_e32 v11, 0, v11
	v_pk_mul_f32 v[16:17], v[16:17], v[16:17]
	v_pk_mul_f32 v[18:19], v[18:19], v[18:19]
	v_pk_mul_f32 v[8:9], v[8:9], v[8:9]
	v_pk_mul_f32 v[10:11], v[10:11], v[10:11]
	v_cvt_pk_bf16_f32 v16, v16, v17
	v_cvt_pk_bf16_f32 v17, v18, v19
	v_cvt_pk_bf16_f32 v18, v8, v9
	v_cvt_pk_bf16_f32 v19, v10, v11
	ds_bpermute_b32 v16, v147, v16
	ds_bpermute_b32 v17, v147, v17
	ds_bpermute_b32 v18, v147, v18
	ds_bpermute_b32 v19, v147, v19
	s_waitcnt lgkmcnt(8)
	global_store_dwordx4 v[166:167], v[48:51], off offset:256 nt
	v_max_f32_e32 v4, 0, v4
	v_max_f32_e32 v5, 0, v5
	v_max_f32_e32 v6, 0, v6
	v_max_f32_e32 v7, 0, v7
	v_max_f32_e32 v0, 0, v0
	v_max_f32_e32 v1, 0, v1
	v_max_f32_e32 v2, 0, v2
	v_max_f32_e32 v3, 0, v3
	v_pk_mul_f32 v[4:5], v[4:5], v[4:5]
	v_pk_mul_f32 v[6:7], v[6:7], v[6:7]
	v_pk_mul_f32 v[0:1], v[0:1], v[0:1]
	v_pk_mul_f32 v[2:3], v[2:3], v[2:3]
	v_cvt_pk_bf16_f32 v4, v4, v5
	v_cvt_pk_bf16_f32 v5, v6, v7
	v_cvt_pk_bf16_f32 v6, v0, v1
	v_cvt_pk_bf16_f32 v7, v2, v3
	ds_bpermute_b32 v4, v147, v4
	ds_bpermute_b32 v5, v147, v5
	ds_bpermute_b32 v6, v147, v6
	ds_bpermute_b32 v7, v147, v7
	s_waitcnt lgkmcnt(8)
	global_store_dwordx4 v[168:169], v[32:35], off offset:256 nt
	s_waitcnt lgkmcnt(4)
	global_store_dwordx4 v[170:171], v[16:19], off offset:256 nt
	s_waitcnt lgkmcnt(0)
	global_store_dwordx4 v[172:173], v[4:7], off offset:256 nt
	s_and_b64 vcc, exec, s[0:1]
	s_mov_b64 s[0:1], -1
	s_cbranch_vccnz .LBB0_948
	s_andn2_b64 vcc, exec, s[20:21]
	s_cbranch_vccnz .LBB0_947
	s_barrier
	s_branch .LBB0_947
